# k50 + prep x-loop row-norm reduction via permlane swaps/DPP instead of 6 serialized ds_bpermute round trips
# baseline (speedup 1.0000x reference)
; DI unsigned pk2(float lo, float hi) { f32x2 x = {lo, hi}; return __builtin_bit_cast(unsigned, __builtin_convertvector(x, bf16x2_t)); }
; DI float sum16(float v) { v += __shfl_xor(v, 8); v += __shfl_xor(v, 4); v += __shfl_xor(v, 2); v += __shfl_xor(v, 1); return v; }
; DI float sum32(float v) { v += __shfl_xor(v, 16); return sum16(v); }
; DI float sum64(float v) { v += __shfl_xor(v, 32); return sum32(v); }
; DI void prep_x(const Params& p, const float* src) {
;     ...
;   for (int row = blockIdx.x * 8 + w; row < MTOK; row += gridDim.x * 8) {
;     const float* xr = src + (size_t)row * DM; f32x4 v[4]; float ss = 0.f;
; #pragma unroll
;     for (int i = 0; i < 4; ++i) { v[i] = *(const f32x4*)(xr + lane * 4 + 256 * i); ss += v[i][0] * v[i][0] + v[i][1] * v[i][1] + v[i][2] * v[i][2] + v[i][3] * v[i][3]; }
;     ss = sum64(ss);
; #pragma unroll
;     for (int i = 0; i < 4; ++i) { u32x2 o; o.x = pk2(v[i][0], v[i][1]); o.y = pk2(v[i][2], v[i][3]); *(u32x2*)(xb + (size_t)row * DM + lane * 4 + 256 * i) = o; }
;     if (lane == 0) rrow[row] = rsqrtf(ss * (1.0f / DM) + EPS);
;   }
.LBB0_64:
	v_ashrrev_i32_e32 v3, 31, v2
	s_waitcnt lgkmcnt(0)
	v_lshlrev_b64 v[16:17], 12, v[2:3]
	v_lshl_add_u64 v[32:33], v[4:5], 0, v[16:17]
	global_load_dwordx4 v[16:19], v[32:33], off
	global_load_dwordx4 v[20:23], v[32:33], off offset:1024
	global_load_dwordx4 v[24:27], v[32:33], off offset:2048
	global_load_dwordx4 v[28:31], v[32:33], off offset:3072
	s_waitcnt vmcnt(3)
	v_mul_f32_e32 v15, v17, v17
	s_waitcnt vmcnt(2)
	v_mul_f32_e32 v32, v21, v21
	s_waitcnt vmcnt(1)
	v_mul_f32_e32 v33, v25, v25
	v_fmac_f32_e32 v15, v16, v16
	v_fmac_f32_e32 v32, v20, v20
	s_waitcnt vmcnt(0)
	v_mul_f32_e32 v34, v29, v29
	v_fmac_f32_e32 v33, v24, v24
	v_fmac_f32_e32 v15, v18, v18
	v_fmac_f32_e32 v32, v22, v22
	v_fmac_f32_e32 v34, v28, v28
	v_fmac_f32_e32 v33, v26, v26
	v_fmac_f32_e32 v15, v19, v19
	v_fmac_f32_e32 v32, v23, v23
	v_fmac_f32_e32 v34, v30, v30
	v_fmac_f32_e32 v33, v27, v27
	v_add_f32_e32 v15, v15, v32
	v_fmac_f32_e32 v34, v31, v31
	v_add_f32_e32 v15, v15, v33
	v_add_f32_e32 v15, v15, v34
	v_cvt_pk_bf16_f32 v16, v16, v17
	v_cvt_pk_bf16_f32 v17, v18, v19
	v_cvt_pk_bf16_f32 v18, v20, v21
	v_cvt_pk_bf16_f32 v19, v22, v23
	v_mov_b32_e32 v32, v15
	s_nop 1
	v_permlane32_swap_b32_e32 v15, v32
	v_add_f32_e32 v15, v15, v32
	v_cvt_pk_bf16_f32 v20, v24, v25
	v_mov_b32_e32 v32, v15
	s_nop 1
	v_permlane16_swap_b32_e32 v15, v32
	v_add_f32_e32 v15, v15, v32
	v_lshlrev_b64 v[32:33], 11, v[2:3]
	v_lshl_add_u64 v[32:33], v[6:7], 0, v[32:33]
	global_store_dwordx2 v[32:33], v[16:17], off
	global_store_dwordx2 v[32:33], v[18:19], off offset:512
	v_cvt_pk_bf16_f32 v18, v28, v29
	v_add_f32_dpp v15, v15, v15 row_ror:8 row_mask:0xf bank_mask:0xf
	v_cvt_pk_bf16_f32 v19, v30, v31
	global_store_dwordx2 v[32:33], v[18:19], off offset:1536
	v_add_f32_dpp v15, v15, v15 row_ror:4 row_mask:0xf bank_mask:0xf
	s_nop 1
	v_add_f32_dpp v15, v15, v15 quad_perm:[2,3,0,1] row_mask:0xf bank_mask:0xf
	s_nop 1
	v_add_f32_dpp v15, v15, v15 quad_perm:[1,0,3,2] row_mask:0xf bank_mask:0xf
	v_cvt_pk_bf16_f32 v21, v26, v27
	global_store_dwordx2 v[32:33], v[20:21], off offset:1024
	s_and_saveexec_b64 s[6:7], vcc
	s_cbranch_execz .LBB0_63
	v_fmamk_f32 v15, v15, 0x3a800000, v14
	v_mul_f32_e32 v16, 0x4b800000, v15
	v_cmp_gt_f32_e64 s[4:5], s9, v15
	s_nop 1
	v_cndmask_b32_e64 v15, v15, v16, s[4:5]
	v_rsq_f32_e32 v15, v15
	s_nop 0
	v_mul_f32_e32 v16, 0x45800000, v15
	v_cndmask_b32_e64 v15, v15, v16, s[4:5]
	v_readlane_b32 s4, v252, 23
	v_readlane_b32 s5, v252, 24
	s_nop 1
	v_lshl_add_u64 v[16:17], v[2:3], 2, s[4:5]
	global_store_dword v[16:17], v15, off
	s_branch .LBB0_63
